# one static s_setprio 1 for waves 4-7 during the attention unit loops (reset at the seam)
# speedup vs baseline: 1.0082x; 1.0082x over previous
.LBB0_430:
	v_readfirstlane_b32 s100, v193
	s_nop 3
	s_lshr_b32 s100, s100, 8
	s_cmp_eq_u32 s100, 1
	s_mov_b32 s100, 0
	s_cbranch_scc0 .Lprio_swa
	s_setprio 1

.LBB0_502:
	s_setprio 0
	s_waitcnt vmcnt(0)
	s_barrier
	s_mov_b64 s[0:1], exec
	v_readlane_b32 s4, v253, 32
	v_readlane_b32 s5, v253, 33
	v_readlane_b32 s52, v255, 40
	s_and_b64 s[4:5], s[0:1], s[4:5]
	v_readlane_b32 s53, v255, 41
	s_mov_b32 s64, s90
	v_readlane_b32 s96, v254, 29
	s_mov_b32 s66, 0x3a800000
	s_mov_b64 s[42:43], 0x60
	s_mov_b64 s[70:71], s[84:85]
	s_mov_b64 exec, s[4:5]
	s_cbranch_execz .LBB0_553
	v_readlane_b32 s4, v255, 36
	s_getreg_b32 s3, hwreg(HW_REG_XCC_ID, 0, 4)
	s_waitcnt vmcnt(0) expcnt(0) lgkmcnt(0)
	v_mov_b32_e32 v0, s4
	ds_read_b32 v2, v0
	v_readlane_b32 s4, v255, 37
	s_waitcnt lgkmcnt(0)
	v_cmp_ne_u32_e32 vcc, 0, v2
	v_mov_b32_e32 v0, s4
	ds_read_b32 v0, v0
	s_cbranch_vccnz .LBB0_517
	s_and_b32 s4, s3, 15
	s_lshl_b32 s9, s4, 8
	s_mov_b32 s10, 0
	s_branch .LBB0_506

.LBB0_986:
	s_setprio 0
	s_waitcnt vmcnt(0)
	s_barrier
	s_mov_b64 s[0:1], exec
	v_readlane_b32 s4, v253, 32
	v_readlane_b32 s5, v253, 33
	s_and_b64 s[4:5], s[0:1], s[4:5]
	s_mov_b64 exec, s[4:5]
	s_cbranch_execz .LBB0_1037
	v_readlane_b32 s4, v255, 36
	s_getreg_b32 s3, hwreg(HW_REG_XCC_ID, 0, 4)
	s_waitcnt vmcnt(0) expcnt(0) lgkmcnt(0)
	v_mov_b32_e32 v0, s4
	ds_read_b32 v2, v0
	v_readlane_b32 s4, v255, 37
	s_waitcnt lgkmcnt(0)
	v_cmp_ne_u32_e32 vcc, 0, v2
	v_mov_b32_e32 v0, s4
	ds_read_b32 v0, v0
	s_cbranch_vccnz .LBB0_1001
	s_and_b32 s4, s3, 15
	s_lshl_b32 s7, s4, 8
	s_mov_b32 s10, 0
	s_branch .LBB0_990
